# conv: hoist loop-top vmcnt(0) out of inner loop (store ack no longer waited per step) + 2.0/x IEEE div sequences -> v_rcp_f32+fma in conv inner loop
# speedup vs baseline: 1.0184x; 1.0184x over previous
.LBB0_152:
	s_or_b64 exec, exec, s[34:35]
	v_lshl_add_u64 v[2:3], v[90:91], 1, s[18:19]
	v_lshl_add_u64 v[142:143], v[88:89], 1, v[2:3]
	global_load_dwordx4 v[128:131], v[142:143], off
	v_add_u32_e32 v234, 2, v116
	s_mov_b64 s[34:35], 0
	s_waitcnt vmcnt(0)
.LBB0_153:
	v_mov_b64_e32 v[118:119], v[98:99]
	v_mov_b64_e32 v[116:117], v[96:97]
	v_mov_b64_e32 v[122:123], v[102:103]
	v_mov_b64_e32 v[126:127], v[94:95]
	v_mov_b64_e32 v[96:97], v[108:109]
	v_mov_b32_e32 v2, v1
	v_mov_b32_e32 v3, v1
	v_mov_b64_e32 v[120:121], v[100:101]
	v_mov_b64_e32 v[124:125], v[92:93]
	v_mov_b64_e32 v[98:99], v[110:111]
	v_mov_b64_e32 v[100:101], v[104:105]
	v_mov_b64_e32 v[94:95], v[78:79]
	v_cmp_lt_u32_e64 s[40:41], v234, v233
	v_mov_b32_e32 v0, v1
	v_mov_b64_e32 v[110:111], v[2:3]
	v_mov_b64_e32 v[102:103], v[106:107]
	v_mov_b64_e32 v[92:93], v[76:77]
	v_lshl_add_u64 v[162:163], v[144:145], 0, s[34:35]
	s_and_b64 s[42:43], s[28:29], s[40:41]
	v_mov_b64_e32 v[108:109], v[0:1]
	s_and_saveexec_b64 s[38:39], s[42:43]
	s_cbranch_execz .LBB0_155
	v_add_co_u32_e32 v76, vcc, 0xfffab000, v162
	s_nop 1
	v_addc_co_u32_e32 v77, vcc, -1, v163, vcc
	global_load_dwordx4 v[108:111], v[76:77], off offset:-1024

.LBB0_159:
	s_or_b64 exec, exec, s[38:39]
	v_add_co_u32_e32 v2, vcc, 0xb581000, v162
	v_lshlrev_b32_e32 v172, 16, v116
	s_nop 0
	v_addc_co_u32_e32 v3, vcc, 0, v163, vcc
	global_load_dwordx4 v[88:91], v[2:3], off offset:1536
	v_lshlrev_b32_e32 v2, 16, v136
	v_and_b32_e32 v3, 0xffff0000, v136
	v_and_b32_e32 v173, 0xffff0000, v116
	v_pk_fma_f32 v[2:3], v[64:65], v[2:3], v[84:85]
	v_lshlrev_b32_e32 v174, 16, v96
	v_pk_fma_f32 v[236:237], v[72:73], v[172:173], v[2:3]
	v_and_b32_e32 v175, 0xffff0000, v96
	v_lshlrev_b32_e32 v238, 16, v132
	v_and_b32_e32 v239, 0xffff0000, v132
	v_pk_fma_f32 v[236:237], v[32:33], v[174:175], v[236:237]
	v_lshlrev_b32_e32 v182, 16, v120
	v_and_b32_e32 v183, 0xffff0000, v120
	v_pk_fma_f32 v[236:237], v[36:37], v[238:239], v[236:237]
	v_lshlrev_b32_e32 v188, 16, v100
	v_and_b32_e32 v189, 0xffff0000, v100
	v_pk_fma_f32 v[236:237], v[40:41], v[182:183], v[236:237]
	v_lshlrev_b32_e32 v238, 16, v112
	v_and_b32_e32 v239, 0xffff0000, v112
	v_pk_fma_f32 v[236:237], v[44:45], v[188:189], v[236:237]
	v_lshlrev_b32_e32 v190, 16, v124
	v_and_b32_e32 v191, 0xffff0000, v124
	v_pk_fma_f32 v[236:237], v[48:49], v[238:239], v[236:237]
	v_lshlrev_b32_e32 v194, 16, v92
	v_and_b32_e32 v195, 0xffff0000, v92
	v_pk_fma_f32 v[236:237], v[52:53], v[190:191], v[236:237]
	v_lshlrev_b32_e32 v238, 16, v128
	v_pk_fma_f32 v[236:237], v[56:57], v[194:195], v[236:237]
	v_and_b32_e32 v239, 0xffff0000, v128
	v_mul_f32_e32 v0, 0x3d372713, v236
	v_mul_f32_e32 v0, v236, v0
	v_fma_f32 v0, v236, v0, v236
	v_mul_f32_e32 v0, 0x3f4c422a, v0
	v_add_f32_e32 v0, v0, v0
	v_mul_f32_e32 v0, 0x3fb8aa3b, v0
	v_exp_f32_e32 v242, v0
	v_mul_f32_e32 v0, 0x3d372713, v237
	v_mul_f32_e32 v0, v237, v0
	v_fma_f32 v0, v237, v0, v237
	v_mul_f32_e32 v0, 0x3f4c422a, v0
	v_add_f32_e32 v0, v0, v0
	v_mul_f32_e32 v0, 0x3fb8aa3b, v0
	v_exp_f32_e32 v243, v0
	v_lshlrev_b32_e32 v2, 16, v137
	v_and_b32_e32 v3, 0xffff0000, v137
	v_lshlrev_b32_e32 v176, 16, v117
	v_pk_add_f32 v[242:243], v[242:243], 1.0 op_sel_hi:[1,0]
	v_and_b32_e32 v177, 0xffff0000, v117
	v_rcp_f32_e32 v243, v243
	v_pk_fma_f32 v[2:3], v[66:67], v[2:3], v[86:87]
	v_lshlrev_b32_e32 v178, 16, v97
	v_pk_fma_f32 v[204:205], v[74:75], v[176:177], v[2:3]
	v_fma_f32 v243, v243, -2.0, 1.0
	v_rcp_f32_e32 v242, v242
	v_and_b32_e32 v179, 0xffff0000, v97
	v_lshlrev_b32_e32 v240, 16, v133
	v_and_b32_e32 v241, 0xffff0000, v133
	v_fma_f32 v242, v242, -2.0, 1.0
	v_pk_mul_f32 v[236:237], v[236:237], 0.5 op_sel_hi:[1,0]
	v_pk_add_f32 v[242:243], v[242:243], 1.0 op_sel_hi:[1,0]
	v_pk_fma_f32 v[204:205], v[34:35], v[178:179], v[204:205]
	v_lshlrev_b32_e32 v164, 16, v121
	v_and_b32_e32 v165, 0xffff0000, v121
	v_pk_mul_f32 v[236:237], v[236:237], v[242:243]
	v_pk_fma_f32 v[204:205], v[38:39], v[240:241], v[204:205]
	v_lshlrev_b32_e32 v166, 16, v101
	v_and_b32_e32 v167, 0xffff0000, v101
	v_pk_mul_f32 v[236:237], v[236:237], v[238:239]
	v_pk_fma_f32 v[204:205], v[42:43], v[164:165], v[204:205]
	v_cvt_pk_bf16_f32 v112, v236, v237
	v_lshlrev_b32_e32 v236, 16, v113
	v_and_b32_e32 v237, 0xffff0000, v113
	v_pk_fma_f32 v[204:205], v[46:47], v[166:167], v[204:205]
	v_lshlrev_b32_e32 v168, 16, v125
	v_and_b32_e32 v169, 0xffff0000, v125
	v_pk_fma_f32 v[204:205], v[50:51], v[236:237], v[204:205]
	v_lshlrev_b32_e32 v170, 16, v93
	v_and_b32_e32 v171, 0xffff0000, v93
	v_pk_fma_f32 v[204:205], v[54:55], v[168:169], v[204:205]
	v_lshlrev_b32_e32 v2, 16, v138
	v_pk_fma_f32 v[204:205], v[58:59], v[170:171], v[204:205]
	v_and_b32_e32 v3, 0xffff0000, v138
	v_mul_f32_e32 v0, 0x3d372713, v204
	v_mul_f32_e32 v0, v204, v0
	v_fma_f32 v0, v204, v0, v204
	v_mul_f32_e32 v0, 0x3f4c422a, v0
	v_add_f32_e32 v0, v0, v0
	v_mul_f32_e32 v0, 0x3fb8aa3b, v0
	v_exp_f32_e32 v236, v0
	v_mul_f32_e32 v0, 0x3d372713, v205
	v_mul_f32_e32 v0, v205, v0
	v_fma_f32 v0, v205, v0, v205
	v_mul_f32_e32 v0, 0x3f4c422a, v0
	v_add_f32_e32 v0, v0, v0
	v_mul_f32_e32 v0, 0x3fb8aa3b, v0
	v_exp_f32_e32 v237, v0
	v_pk_mul_f32 v[204:205], v[204:205], 0.5 op_sel_hi:[1,0]
	v_lshlrev_b32_e32 v180, 16, v118
	v_and_b32_e32 v181, 0xffff0000, v118
	v_pk_add_f32 v[236:237], v[236:237], 1.0 op_sel_hi:[1,0]
	v_pk_fma_f32 v[2:3], v[60:61], v[2:3], v[80:81]
	v_rcp_f32_e32 v237, v237
	v_lshlrev_b32_e32 v128, 16, v129
	v_and_b32_e32 v129, 0xffff0000, v129
	v_pk_fma_f32 v[200:201], v[68:69], v[180:181], v[2:3]
	v_fma_f32 v237, v237, -2.0, 1.0
	v_rcp_f32_e32 v236, v236
	v_lshlrev_b32_e32 v184, 16, v98
	v_and_b32_e32 v185, 0xffff0000, v98
	v_lshlrev_b32_e32 v202, 16, v134
	v_fma_f32 v236, v236, -2.0, 1.0
	v_and_b32_e32 v203, 0xffff0000, v134
	v_pk_add_f32 v[236:237], v[236:237], 1.0 op_sel_hi:[1,0]
	v_lshlrev_b32_e32 v2, 16, v139
	v_pk_mul_f32 v[204:205], v[204:205], v[236:237]
	v_and_b32_e32 v3, 0xffff0000, v139
	v_pk_mul_f32 v[128:129], v[204:205], v[128:129]
	v_lshlrev_b32_e32 v138, 16, v122
	v_cvt_pk_bf16_f32 v113, v128, v129
	v_pk_fma_f32 v[128:129], v[4:5], v[184:185], v[200:201]
	v_and_b32_e32 v139, 0xffff0000, v122
	v_pk_fma_f32 v[128:129], v[8:9], v[202:203], v[128:129]
	v_lshlrev_b32_e32 v146, 16, v102
	v_and_b32_e32 v147, 0xffff0000, v102
	v_pk_fma_f32 v[128:129], v[12:13], v[138:139], v[128:129]
	v_lshlrev_b32_e32 v200, 16, v114
	v_and_b32_e32 v201, 0xffff0000, v114
	v_pk_fma_f32 v[128:129], v[16:17], v[146:147], v[128:129]
	v_lshlrev_b32_e32 v148, 16, v126
	v_and_b32_e32 v149, 0xffff0000, v126
	v_pk_fma_f32 v[128:129], v[20:21], v[200:201], v[128:129]
	v_lshlrev_b32_e32 v160, 16, v94
	v_and_b32_e32 v161, 0xffff0000, v94
	v_pk_fma_f32 v[128:129], v[24:25], v[148:149], v[128:129]
	v_lshlrev_b32_e32 v200, 16, v130
	v_pk_fma_f32 v[128:129], v[28:29], v[160:161], v[128:129]
	v_and_b32_e32 v201, 0xffff0000, v130
	v_mul_f32_e32 v0, 0x3d372713, v128
	v_mul_f32_e32 v0, v128, v0
	v_fma_f32 v0, v128, v0, v128
	v_mul_f32_e32 v0, 0x3f4c422a, v0
	v_add_f32_e32 v0, v0, v0
	v_mul_f32_e32 v0, 0x3fb8aa3b, v0
	v_exp_f32_e32 v202, v0
	v_mul_f32_e32 v0, 0x3d372713, v129
	v_mul_f32_e32 v0, v129, v0
	v_fma_f32 v0, v129, v0, v129
	v_mul_f32_e32 v0, 0x3f4c422a, v0
	v_add_f32_e32 v0, v0, v0
	v_mul_f32_e32 v0, 0x3fb8aa3b, v0
	v_exp_f32_e32 v203, v0
	v_pk_mul_f32 v[128:129], v[128:129], 0.5 op_sel_hi:[1,0]
	v_lshlrev_b32_e32 v186, 16, v119
	v_and_b32_e32 v187, 0xffff0000, v119
	v_pk_add_f32 v[202:203], v[202:203], 1.0 op_sel_hi:[1,0]
	v_pk_fma_f32 v[2:3], v[62:63], v[2:3], v[82:83]
	v_rcp_f32_e32 v203, v203
	v_pk_fma_f32 v[196:197], v[70:71], v[186:187], v[2:3]
	v_lshlrev_b32_e32 v192, 16, v99
	v_and_b32_e32 v193, 0xffff0000, v99
	v_fma_f32 v203, v203, -2.0, 1.0
	v_rcp_f32_e32 v202, v202
	v_lshlrev_b32_e32 v198, 16, v135
	v_and_b32_e32 v199, 0xffff0000, v135
	v_lshlrev_b32_e32 v2, 16, v123
	v_fma_f32 v202, v202, -2.0, 1.0
	v_and_b32_e32 v3, 0xffff0000, v123
	v_pk_add_f32 v[202:203], v[202:203], 1.0 op_sel_hi:[1,0]
	v_lshlrev_b32_e32 v132, 16, v103
	v_pk_mul_f32 v[128:129], v[128:129], v[202:203]
	v_and_b32_e32 v133, 0xffff0000, v103
	v_pk_mul_f32 v[128:129], v[128:129], v[200:201]
	v_lshlrev_b32_e32 v134, 16, v127
	v_cvt_pk_bf16_f32 v114, v128, v129
	v_pk_fma_f32 v[128:129], v[6:7], v[192:193], v[196:197]
	v_lshlrev_b32_e32 v196, 16, v115
	v_pk_fma_f32 v[128:129], v[10:11], v[198:199], v[128:129]
	v_and_b32_e32 v197, 0xffff0000, v115
	v_pk_fma_f32 v[128:129], v[14:15], v[2:3], v[128:129]
	v_and_b32_e32 v135, 0xffff0000, v127
	v_pk_fma_f32 v[128:129], v[18:19], v[132:133], v[128:129]
	v_lshlrev_b32_e32 v136, 16, v95
	v_pk_fma_f32 v[128:129], v[22:23], v[196:197], v[128:129]
	v_and_b32_e32 v137, 0xffff0000, v95
	v_pk_fma_f32 v[128:129], v[26:27], v[134:135], v[128:129]
	v_lshlrev_b32_e32 v130, 16, v131
	v_pk_fma_f32 v[128:129], v[30:31], v[136:137], v[128:129]
	v_and_b32_e32 v131, 0xffff0000, v131
	v_mul_f32_e32 v0, 0x3d372713, v128
	v_mul_f32_e32 v0, v128, v0
	v_fma_f32 v0, v128, v0, v128
	v_mul_f32_e32 v0, 0x3f4c422a, v0
	v_add_f32_e32 v0, v0, v0
	v_mul_f32_e32 v0, 0x3fb8aa3b, v0
	v_exp_f32_e32 v196, v0
	v_mul_f32_e32 v0, 0x3d372713, v129
	v_mul_f32_e32 v0, v129, v0
	v_fma_f32 v0, v129, v0, v129
	v_mul_f32_e32 v0, 0x3f4c422a, v0
	v_add_f32_e32 v0, v0, v0
	v_mul_f32_e32 v0, 0x3fb8aa3b, v0
	v_exp_f32_e32 v197, v0
	v_pk_mul_f32 v[128:129], v[128:129], 0.5 op_sel_hi:[1,0]
	s_add_u32 s34, s34, 0x1600
	s_addc_u32 s35, s35, 0
	v_pk_add_f32 v[196:197], v[196:197], 1.0 op_sel_hi:[1,0]
	v_add_u32_e32 v234, 1, v234
	v_rcp_f32_e32 v197, v197
	s_cmp_eq_u32 s34, 0x2aa00
	v_fma_f32 v197, v197, -2.0, 1.0
	v_rcp_f32_e32 v196, v196
	s_mov_b32 s38, 0xb580000
	v_fma_f32 v196, v196, -2.0, 1.0
	s_nop 0
	v_pk_add_f32 v[196:197], v[196:197], 1.0 op_sel_hi:[1,0]
	s_nop 0
	v_pk_mul_f32 v[128:129], v[128:129], v[196:197]
	s_nop 0
	v_pk_mul_f32 v[128:129], v[128:129], v[130:131]
	s_nop 0
	v_cvt_pk_bf16_f32 v115, v128, v129
	v_add_co_u32_e32 v128, vcc, s38, v162
	s_nop 1
	v_addc_co_u32_e32 v129, vcc, 0, v163, vcc
	global_store_dwordx4 v[128:129], v[112:115], off
	s_cbranch_scc1 .LBB0_131
	s_nop 0
	v_mov_b64_e32 v[112:113], v[124:125]
	v_mov_b64_e32 v[134:135], v[122:123]
	v_mov_b64_e32 v[138:139], v[118:119]
	s_waitcnt vmcnt(1)
	v_mov_b64_e32 v[130:131], v[90:91]
	v_mov_b64_e32 v[114:115], v[126:127]
	v_mov_b64_e32 v[132:133], v[120:121]
	v_mov_b64_e32 v[136:137], v[116:117]
	v_mov_b64_e32 v[128:129], v[88:89]
	s_branch .LBB0_153
